# prep compress_item: W rows also staged through a wave-private LDS region with full-line global loads (no extra barrier), fragments read back with ds_read_b128
# baseline (speedup 1.0000x reference)
; DI void compress_item(const Args& a, int l, int item, LAS unsigned char* lds) {
;     ...
;     const bf16_t* w1 = W + W_C1 + (size_t)kv * 262144 + (size_t)(wid * 16 + fr) * 2048 + fq * 8;
;     int tk0[2];
; #pragma unroll
;     for (int m = 0; m < 2; ++m) tk0[m] = 16 * (nq * 32 + m * 16 + fr);
; #pragma unroll 1
;     for (int k8 = 0; k8 < 64; k8 += 8) {
;         bf16x8 bfr[8], af[8][2];
; #pragma unroll
;         for (int kk = 0; kk < 8; ++kk) {
;             const int ks = k8 + kk, tokoff = ks >> 1, dcol = (ks & 1) * 32 + fq * 8;
;             bfr[kk] = *(const bf16x8*)(w1 + ks * 32);
; #pragma unroll
;             for (int m = 0; m < 2; ++m) { int tk = tk0[m] + tokoff; tk = tk > SEQ - 1 ? SEQ - 1 : tk; af[kk][m] = *(const bf16x8*)(PROJ + ((size_t)b * SEQ + tk) * PP + colbase + dcol); }
.LBB0_604:
	s_and_b32 s14, s10, 7
	s_lshl_b32 s14, s14, 9
	v_bfe_u32 v181, v9, 5, 4
	v_bfe_u32 v182, v9, 3, 2
	v_and_b32_e32 v183, 7, v9
	v_lshl_add_u32 v178, v181, 4, v182
	v_add_u32_e32 v178, s14, v178
	v_lshlrev_b32_e32 v176, 4, v183
	v_sub_u32_e32 v176, v176, v12
	v_ashrrev_i32_e32 v177, 31, v176
	v_lshl_add_u64 v[252:253], v[14:15], 0, v[176:177]
	v_mul_u32_u24_e32 v179, 544, v181
	v_lshl_add_u32 v179, v182, 7, v179
	v_lshl_add_u32 v179, v183, 4, v179
	v_add_u32_e32 v179, 0x11000, v179
	v_mul_u32_u24_e32 v180, 544, v21
	v_lshl_add_u32 v180, v20, 4, v180
	v_add_u32_e32 v180, 0x11000, v180
	v_bfe_u32 v181, v9, 5, 1
	v_and_b32_e32 v182, 31, v9
	v_sub_u32_e32 v176, v181, v21
	v_lshlrev_b32_e32 v176, 12, v176
	v_lshl_add_u32 v176, v182, 4, v176
	v_add_u32_e32 v176, 0xffffff00, v176
	v_ashrrev_i32_e32 v177, 31, v176
	v_lshl_add_u64 v[184:185], v[18:19], 0, v[176:177]
	v_lshrrev_b32_e32 v183, 6, v9
	v_mul_u32_u24_e32 v183, 8704, v183
	v_mul_u32_u24_e32 v186, 544, v181
	v_lshl_add_u32 v186, v182, 4, v186
	v_add_u32_e32 v186, v183, v186
	v_mul_u32_u24_e32 v187, 544, v21
	v_lshl_add_u32 v187, v20, 4, v187
	v_add_u32_e32 v187, v183, v187
	v_add_u32_e32 v251, 0, v178
	v_min_u32_e32 v251, 0xfff, v251
	v_or_b32_e32 v251, s6, v251
	v_mul_u32_u24_e32 v128, 0x1830, v251
	v_lshl_add_u64 v[254:255], v[252:253], 0, v[128:129]
	global_load_dwordx4 v[168:171], v[254:255], off
	v_add_u32_e32 v251, 0x100, v178
	v_min_u32_e32 v251, 0xfff, v251
	v_or_b32_e32 v251, s6, v251
	v_mul_u32_u24_e32 v128, 0x1830, v251
	v_lshl_add_u64 v[254:255], v[252:253], 0, v[128:129]
	global_load_dwordx4 v[172:175], v[254:255], off
	global_load_dwordx4 v[24:27], v[184:185], off
	s_mov_b64 s[14:15], 0x2000
	v_lshl_add_u64 v[254:255], v[184:185], 0, s[14:15]
	global_load_dwordx4 v[28:31], v[254:255], off
	s_mov_b64 s[14:15], 0x4000
	v_lshl_add_u64 v[254:255], v[184:185], 0, s[14:15]
	global_load_dwordx4 v[32:35], v[254:255], off
	s_mov_b64 s[14:15], 0x6000
	v_lshl_add_u64 v[254:255], v[184:185], 0, s[14:15]
	global_load_dwordx4 v[36:39], v[254:255], off
	s_mov_b64 s[14:15], 0x8000
	v_lshl_add_u64 v[254:255], v[184:185], 0, s[14:15]
	global_load_dwordx4 v[40:43], v[254:255], off
	s_mov_b64 s[14:15], 0xa000
	v_lshl_add_u64 v[254:255], v[184:185], 0, s[14:15]
	global_load_dwordx4 v[44:47], v[254:255], off
	s_mov_b64 s[14:15], 0xc000
	v_lshl_add_u64 v[254:255], v[184:185], 0, s[14:15]
	global_load_dwordx4 v[48:51], v[254:255], off
	s_mov_b64 s[14:15], 0xe000
	v_lshl_add_u64 v[254:255], v[184:185], 0, s[14:15]
	global_load_dwordx4 v[52:55], v[254:255], off
	s_waitcnt vmcnt(8)
	ds_write_b128 v179, v[168:171] offset:0
	ds_write_b128 v179, v[172:175] offset:8704
	s_waitcnt vmcnt(7)
	ds_write_b128 v186, v[24:27] offset:0
	s_waitcnt vmcnt(6)
	ds_write_b128 v186, v[28:31] offset:1088
	s_waitcnt vmcnt(5)
	ds_write_b128 v186, v[32:35] offset:2176
	s_waitcnt vmcnt(4)
	ds_write_b128 v186, v[36:39] offset:3264
	s_waitcnt vmcnt(3)
	ds_write_b128 v186, v[40:43] offset:4352
	s_waitcnt vmcnt(2)
	ds_write_b128 v186, v[44:47] offset:5440
	s_waitcnt vmcnt(1)
	ds_write_b128 v186, v[48:51] offset:6528
	s_waitcnt vmcnt(0)
	ds_write_b128 v186, v[52:55] offset:7616
	v_add_u32_e32 v251, 4, v178
	v_min_u32_e32 v251, 0xfff, v251
	v_or_b32_e32 v251, s6, v251
	v_mul_u32_u24_e32 v128, 0x1830, v251
	v_lshl_add_u64 v[254:255], v[252:253], 0, v[128:129]
	global_load_dwordx4 v[168:171], v[254:255], off
	v_add_u32_e32 v251, 0x104, v178
	v_min_u32_e32 v251, 0xfff, v251
	v_or_b32_e32 v251, s6, v251
	v_mul_u32_u24_e32 v128, 0x1830, v251
	v_lshl_add_u64 v[254:255], v[252:253], 0, v[128:129]
	global_load_dwordx4 v[172:175], v[254:255], off
	s_mov_b64 s[14:15], 0x200
	v_lshl_add_u64 v[254:255], v[184:185], 0, s[14:15]
	global_load_dwordx4 v[24:27], v[254:255], off
	s_mov_b64 s[14:15], 0x2200
	v_lshl_add_u64 v[254:255], v[184:185], 0, s[14:15]
	global_load_dwordx4 v[28:31], v[254:255], off
	s_mov_b64 s[14:15], 0x4200
	v_lshl_add_u64 v[254:255], v[184:185], 0, s[14:15]
	global_load_dwordx4 v[32:35], v[254:255], off
	s_mov_b64 s[14:15], 0x6200
	v_lshl_add_u64 v[254:255], v[184:185], 0, s[14:15]
	global_load_dwordx4 v[36:39], v[254:255], off
	s_mov_b64 s[14:15], 0x8200
	v_lshl_add_u64 v[254:255], v[184:185], 0, s[14:15]
	global_load_dwordx4 v[40:43], v[254:255], off
	s_mov_b64 s[14:15], 0xa200
	v_lshl_add_u64 v[254:255], v[184:185], 0, s[14:15]
	global_load_dwordx4 v[44:47], v[254:255], off
	s_mov_b64 s[14:15], 0xc200
	v_lshl_add_u64 v[254:255], v[184:185], 0, s[14:15]
	global_load_dwordx4 v[48:51], v[254:255], off
	s_mov_b64 s[14:15], 0xe200
	v_lshl_add_u64 v[254:255], v[184:185], 0, s[14:15]
	global_load_dwordx4 v[52:55], v[254:255], off
	s_waitcnt lgkmcnt(0)
	s_barrier
; #define MFMA16(a, b, c) __builtin_amdgcn_mfma_f32_16x16x32_bf16((a), (b), (c), 0, 0, 0)
; DI void compress_item(const Args& a, int l, int item, LAS unsigned char* lds) {
;     ...
; #pragma unroll 1
;     for (int k8 = 0; k8 < 64; k8 += 8) {
;         bf16x8 bfr[8], af[8][2];
; #pragma unroll
;         for (int kk = 0; kk < 8; ++kk) {
;             const int ks = k8 + kk, tokoff = ks >> 1, dcol = (ks & 1) * 32 + fq * 8;
;             bfr[kk] = *(const bf16x8*)(w1 + ks * 32);
; #pragma unroll
;             for (int m = 0; m < 2; ++m) { int tk = tk0[m] + tokoff; tk = tk > SEQ - 1 ? SEQ - 1 : tk; af[kk][m] = *(const bf16x8*)(PROJ + ((size_t)b * SEQ + tk) * PP + colbase + dcol); }
;         }
; #pragma unroll
;         for (int kk = 0; kk < 8; ++kk)
; #pragma unroll
;             for (int m = 0; m < 2; ++m) acc[m] = MFMA16(af[kk][m], bfr[kk], acc[m]);
;     }
	ds_read_b128 v[88:91], v180 offset:0
	ds_read_b128 v[92:95], v180 offset:8704
	ds_read_b128 v[56:59], v187 offset:0
	ds_read_b128 v[96:99], v180 offset:64
	ds_read_b128 v[100:103], v180 offset:8768
	ds_read_b128 v[60:63], v187 offset:64
	ds_read_b128 v[104:107], v180 offset:128
	ds_read_b128 v[108:111], v180 offset:8832
	ds_read_b128 v[64:67], v187 offset:128
	ds_read_b128 v[112:115], v180 offset:192
	ds_read_b128 v[116:119], v180 offset:8896
	ds_read_b128 v[68:71], v187 offset:192
	ds_read_b128 v[120:123], v180 offset:256
	ds_read_b128 v[124:127], v180 offset:8960
	ds_read_b128 v[72:75], v187 offset:256
	ds_read_b128 v[130:133], v180 offset:320
	ds_read_b128 v[134:137], v180 offset:9024
	ds_read_b128 v[76:79], v187 offset:320
	ds_read_b128 v[138:141], v180 offset:384
	ds_read_b128 v[142:145], v180 offset:9088
	ds_read_b128 v[80:83], v187 offset:384
	ds_read_b128 v[146:149], v180 offset:448
	ds_read_b128 v[150:153], v180 offset:9152
	ds_read_b128 v[84:87], v187 offset:448
	s_waitcnt lgkmcnt(15)
	v_mfma_f32_16x16x32_bf16 v[4:7], v[88:91], v[56:59], v[4:7]
	v_mfma_f32_16x16x32_bf16 v[0:3], v[92:95], v[56:59], v[0:3]
	s_waitcnt lgkmcnt(15)
	v_mfma_f32_16x16x32_bf16 v[4:7], v[96:99], v[60:63], v[4:7]
	v_mfma_f32_16x16x32_bf16 v[0:3], v[100:103], v[60:63], v[0:3]
	s_waitcnt lgkmcnt(15)
	v_mfma_f32_16x16x32_bf16 v[4:7], v[104:107], v[64:67], v[4:7]
	v_mfma_f32_16x16x32_bf16 v[0:3], v[108:111], v[64:67], v[0:3]
	s_waitcnt lgkmcnt(12)
	v_mfma_f32_16x16x32_bf16 v[4:7], v[112:115], v[68:71], v[4:7]
	v_mfma_f32_16x16x32_bf16 v[0:3], v[116:119], v[68:71], v[0:3]
	s_waitcnt lgkmcnt(9)
	v_mfma_f32_16x16x32_bf16 v[4:7], v[120:123], v[72:75], v[4:7]
	v_mfma_f32_16x16x32_bf16 v[0:3], v[124:127], v[72:75], v[0:3]
	s_waitcnt lgkmcnt(6)
	v_mfma_f32_16x16x32_bf16 v[4:7], v[130:133], v[76:79], v[4:7]
	v_mfma_f32_16x16x32_bf16 v[0:3], v[134:137], v[76:79], v[0:3]
	s_waitcnt lgkmcnt(3)
	v_mfma_f32_16x16x32_bf16 v[4:7], v[138:141], v[80:83], v[4:7]
	v_mfma_f32_16x16x32_bf16 v[0:3], v[142:145], v[80:83], v[0:3]
	s_waitcnt lgkmcnt(0)
	v_mfma_f32_16x16x32_bf16 v[4:7], v[146:149], v[84:87], v[4:7]
	v_mfma_f32_16x16x32_bf16 v[0:3], v[150:153], v[84:87], v[0:3]
	s_waitcnt vmcnt(7)
	ds_write_b128 v186, v[24:27] offset:0
	s_waitcnt vmcnt(6)
	ds_write_b128 v186, v[28:31] offset:1088
	s_waitcnt vmcnt(5)
	ds_write_b128 v186, v[32:35] offset:2176
	s_waitcnt vmcnt(4)
	ds_write_b128 v186, v[36:39] offset:3264
	s_waitcnt vmcnt(3)
	ds_write_b128 v186, v[40:43] offset:4352
	s_waitcnt vmcnt(2)
	ds_write_b128 v186, v[44:47] offset:5440
	s_waitcnt vmcnt(1)
	ds_write_b128 v186, v[48:51] offset:6528
	s_waitcnt vmcnt(0)
	ds_write_b128 v186, v[52:55] offset:7616
	s_mov_b64 s[14:15], 0x400
	v_lshl_add_u64 v[254:255], v[184:185], 0, s[14:15]
	global_load_dwordx4 v[24:27], v[254:255], off
	s_mov_b64 s[14:15], 0x2400
	v_lshl_add_u64 v[254:255], v[184:185], 0, s[14:15]
	global_load_dwordx4 v[28:31], v[254:255], off
	s_mov_b64 s[14:15], 0x4400
	v_lshl_add_u64 v[254:255], v[184:185], 0, s[14:15]
	global_load_dwordx4 v[32:35], v[254:255], off
	s_mov_b64 s[14:15], 0x6400
	v_lshl_add_u64 v[254:255], v[184:185], 0, s[14:15]
	global_load_dwordx4 v[36:39], v[254:255], off
	s_mov_b64 s[14:15], 0x8400
	v_lshl_add_u64 v[254:255], v[184:185], 0, s[14:15]
	global_load_dwordx4 v[40:43], v[254:255], off
	s_mov_b64 s[14:15], 0xa400
	v_lshl_add_u64 v[254:255], v[184:185], 0, s[14:15]
	global_load_dwordx4 v[44:47], v[254:255], off
	s_mov_b64 s[14:15], 0xc400
	v_lshl_add_u64 v[254:255], v[184:185], 0, s[14:15]
	global_load_dwordx4 v[48:51], v[254:255], off
	s_mov_b64 s[14:15], 0xe400
	v_lshl_add_u64 v[254:255], v[184:185], 0, s[14:15]
	global_load_dwordx4 v[52:55], v[254:255], off
	s_waitcnt vmcnt(16)
	ds_write_b128 v179, v[168:171] offset:17408
	ds_write_b128 v179, v[172:175] offset:26112
	v_add_u32_e32 v251, 8, v178
	v_min_u32_e32 v251, 0xfff, v251
	v_or_b32_e32 v251, s6, v251
	v_mul_u32_u24_e32 v128, 0x1830, v251
	v_lshl_add_u64 v[254:255], v[252:253], 0, v[128:129]
	global_load_dwordx4 v[168:171], v[254:255], off
	v_add_u32_e32 v251, 0x108, v178
	v_min_u32_e32 v251, 0xfff, v251
	v_or_b32_e32 v251, s6, v251
	v_mul_u32_u24_e32 v128, 0x1830, v251
	v_lshl_add_u64 v[254:255], v[252:253], 0, v[128:129]
	global_load_dwordx4 v[172:175], v[254:255], off
	s_waitcnt lgkmcnt(0)
	s_barrier
; #define MFMA16(a, b, c) __builtin_amdgcn_mfma_f32_16x16x32_bf16((a), (b), (c), 0, 0, 0)
; DI void compress_item(const Args& a, int l, int item, LAS unsigned char* lds) {
;     ...
; #pragma unroll 1
;     for (int k8 = 0; k8 < 64; k8 += 8) {
;         bf16x8 bfr[8], af[8][2];
; #pragma unroll
;         for (int kk = 0; kk < 8; ++kk) {
;             const int ks = k8 + kk, tokoff = ks >> 1, dcol = (ks & 1) * 32 + fq * 8;
;             bfr[kk] = *(const bf16x8*)(w1 + ks * 32);
; #pragma unroll
;             for (int m = 0; m < 2; ++m) { int tk = tk0[m] + tokoff; tk = tk > SEQ - 1 ? SEQ - 1 : tk; af[kk][m] = *(const bf16x8*)(PROJ + ((size_t)b * SEQ + tk) * PP + colbase + dcol); }
;         }
; #pragma unroll
;         for (int kk = 0; kk < 8; ++kk)
; #pragma unroll
;             for (int m = 0; m < 2; ++m) acc[m] = MFMA16(af[kk][m], bfr[kk], acc[m]);
;     }
	ds_read_b128 v[88:91], v180 offset:17408
	ds_read_b128 v[92:95], v180 offset:26112
	ds_read_b128 v[56:59], v187 offset:0
	ds_read_b128 v[96:99], v180 offset:17472
	ds_read_b128 v[100:103], v180 offset:26176
	ds_read_b128 v[60:63], v187 offset:64
	ds_read_b128 v[104:107], v180 offset:17536
	ds_read_b128 v[108:111], v180 offset:26240
	ds_read_b128 v[64:67], v187 offset:128
	ds_read_b128 v[112:115], v180 offset:17600
	ds_read_b128 v[116:119], v180 offset:26304
	ds_read_b128 v[68:71], v187 offset:192
	ds_read_b128 v[120:123], v180 offset:17664
	ds_read_b128 v[124:127], v180 offset:26368
	ds_read_b128 v[72:75], v187 offset:256
	ds_read_b128 v[130:133], v180 offset:17728
	ds_read_b128 v[134:137], v180 offset:26432
	ds_read_b128 v[76:79], v187 offset:320
	ds_read_b128 v[138:141], v180 offset:17792
	ds_read_b128 v[142:145], v180 offset:26496
	ds_read_b128 v[80:83], v187 offset:384
	ds_read_b128 v[146:149], v180 offset:17856
	ds_read_b128 v[150:153], v180 offset:26560
	ds_read_b128 v[84:87], v187 offset:448
	s_waitcnt lgkmcnt(15)
	v_mfma_f32_16x16x32_bf16 v[4:7], v[88:91], v[56:59], v[4:7]
	v_mfma_f32_16x16x32_bf16 v[0:3], v[92:95], v[56:59], v[0:3]
	s_waitcnt lgkmcnt(15)
	v_mfma_f32_16x16x32_bf16 v[4:7], v[96:99], v[60:63], v[4:7]
	v_mfma_f32_16x16x32_bf16 v[0:3], v[100:103], v[60:63], v[0:3]
	s_waitcnt lgkmcnt(15)
	v_mfma_f32_16x16x32_bf16 v[4:7], v[104:107], v[64:67], v[4:7]
	v_mfma_f32_16x16x32_bf16 v[0:3], v[108:111], v[64:67], v[0:3]
	s_waitcnt lgkmcnt(12)
	v_mfma_f32_16x16x32_bf16 v[4:7], v[112:115], v[68:71], v[4:7]
	v_mfma_f32_16x16x32_bf16 v[0:3], v[116:119], v[68:71], v[0:3]
	s_waitcnt lgkmcnt(9)
	v_mfma_f32_16x16x32_bf16 v[4:7], v[120:123], v[72:75], v[4:7]
	v_mfma_f32_16x16x32_bf16 v[0:3], v[124:127], v[72:75], v[0:3]
	s_waitcnt lgkmcnt(6)
	v_mfma_f32_16x16x32_bf16 v[4:7], v[130:133], v[76:79], v[4:7]
	v_mfma_f32_16x16x32_bf16 v[0:3], v[134:137], v[76:79], v[0:3]
	s_waitcnt lgkmcnt(3)
	v_mfma_f32_16x16x32_bf16 v[4:7], v[138:141], v[80:83], v[4:7]
	v_mfma_f32_16x16x32_bf16 v[0:3], v[142:145], v[80:83], v[0:3]
	s_waitcnt lgkmcnt(0)
	v_mfma_f32_16x16x32_bf16 v[4:7], v[146:149], v[84:87], v[4:7]
	v_mfma_f32_16x16x32_bf16 v[0:3], v[150:153], v[84:87], v[0:3]
	s_waitcnt vmcnt(9)
	ds_write_b128 v186, v[24:27] offset:0
	s_waitcnt vmcnt(8)
	ds_write_b128 v186, v[28:31] offset:1088
	s_waitcnt vmcnt(7)
	ds_write_b128 v186, v[32:35] offset:2176
	s_waitcnt vmcnt(6)
	ds_write_b128 v186, v[36:39] offset:3264
	s_waitcnt vmcnt(5)
	ds_write_b128 v186, v[40:43] offset:4352
	s_waitcnt vmcnt(4)
	ds_write_b128 v186, v[44:47] offset:5440
	s_waitcnt vmcnt(3)
	ds_write_b128 v186, v[48:51] offset:6528
	s_waitcnt vmcnt(2)
	ds_write_b128 v186, v[52:55] offset:7616
	s_mov_b64 s[14:15], 0x600
	v_lshl_add_u64 v[254:255], v[184:185], 0, s[14:15]
	global_load_dwordx4 v[24:27], v[254:255], off
	s_mov_b64 s[14:15], 0x2600
	v_lshl_add_u64 v[254:255], v[184:185], 0, s[14:15]
	global_load_dwordx4 v[28:31], v[254:255], off
	s_mov_b64 s[14:15], 0x4600
	v_lshl_add_u64 v[254:255], v[184:185], 0, s[14:15]
	global_load_dwordx4 v[32:35], v[254:255], off
	s_mov_b64 s[14:15], 0x6600
	v_lshl_add_u64 v[254:255], v[184:185], 0, s[14:15]
	global_load_dwordx4 v[36:39], v[254:255], off
	s_mov_b64 s[14:15], 0x8600
	v_lshl_add_u64 v[254:255], v[184:185], 0, s[14:15]
	global_load_dwordx4 v[40:43], v[254:255], off
	s_mov_b64 s[14:15], 0xa600
	v_lshl_add_u64 v[254:255], v[184:185], 0, s[14:15]
	global_load_dwordx4 v[44:47], v[254:255], off
	s_mov_b64 s[14:15], 0xc600
	v_lshl_add_u64 v[254:255], v[184:185], 0, s[14:15]
	global_load_dwordx4 v[48:51], v[254:255], off
	s_mov_b64 s[14:15], 0xe600
	v_lshl_add_u64 v[254:255], v[184:185], 0, s[14:15]
	global_load_dwordx4 v[52:55], v[254:255], off
	s_waitcnt vmcnt(8)
	ds_write_b128 v179, v[168:171] offset:0
	ds_write_b128 v179, v[172:175] offset:8704
	v_add_u32_e32 v251, 12, v178
	v_min_u32_e32 v251, 0xfff, v251
	v_or_b32_e32 v251, s6, v251
	v_mul_u32_u24_e32 v128, 0x1830, v251
	v_lshl_add_u64 v[254:255], v[252:253], 0, v[128:129]
	global_load_dwordx4 v[168:171], v[254:255], off
	v_add_u32_e32 v251, 0x10c, v178
	v_min_u32_e32 v251, 0xfff, v251
	v_or_b32_e32 v251, s6, v251
	v_mul_u32_u24_e32 v128, 0x1830, v251
	v_lshl_add_u64 v[254:255], v[252:253], 0, v[128:129]
	global_load_dwordx4 v[172:175], v[254:255], off
	s_waitcnt lgkmcnt(0)
	s_barrier
; #define MFMA16(a, b, c) __builtin_amdgcn_mfma_f32_16x16x32_bf16((a), (b), (c), 0, 0, 0)
; DI void compress_item(const Args& a, int l, int item, LAS unsigned char* lds) {
;     ...
; #pragma unroll 1
;     for (int k8 = 0; k8 < 64; k8 += 8) {
;         bf16x8 bfr[8], af[8][2];
; #pragma unroll
;         for (int kk = 0; kk < 8; ++kk) {
;             const int ks = k8 + kk, tokoff = ks >> 1, dcol = (ks & 1) * 32 + fq * 8;
;             bfr[kk] = *(const bf16x8*)(w1 + ks * 32);
; #pragma unroll
;             for (int m = 0; m < 2; ++m) { int tk = tk0[m] + tokoff; tk = tk > SEQ - 1 ? SEQ - 1 : tk; af[kk][m] = *(const bf16x8*)(PROJ + ((size_t)b * SEQ + tk) * PP + colbase + dcol); }
;         }
; #pragma unroll
;         for (int kk = 0; kk < 8; ++kk)
; #pragma unroll
;             for (int m = 0; m < 2; ++m) acc[m] = MFMA16(af[kk][m], bfr[kk], acc[m]);
;     }
	ds_read_b128 v[88:91], v180 offset:0
	ds_read_b128 v[92:95], v180 offset:8704
	ds_read_b128 v[56:59], v187 offset:0
	ds_read_b128 v[96:99], v180 offset:64
	ds_read_b128 v[100:103], v180 offset:8768
	ds_read_b128 v[60:63], v187 offset:64
	ds_read_b128 v[104:107], v180 offset:128
	ds_read_b128 v[108:111], v180 offset:8832
	ds_read_b128 v[64:67], v187 offset:128
	ds_read_b128 v[112:115], v180 offset:192
	ds_read_b128 v[116:119], v180 offset:8896
	ds_read_b128 v[68:71], v187 offset:192
	ds_read_b128 v[120:123], v180 offset:256
	ds_read_b128 v[124:127], v180 offset:8960
	ds_read_b128 v[72:75], v187 offset:256
	ds_read_b128 v[130:133], v180 offset:320
	ds_read_b128 v[134:137], v180 offset:9024
	ds_read_b128 v[76:79], v187 offset:320
	ds_read_b128 v[138:141], v180 offset:384
	ds_read_b128 v[142:145], v180 offset:9088
	ds_read_b128 v[80:83], v187 offset:384
	ds_read_b128 v[146:149], v180 offset:448
	ds_read_b128 v[150:153], v180 offset:9152
	ds_read_b128 v[84:87], v187 offset:448
	s_waitcnt lgkmcnt(15)
	v_mfma_f32_16x16x32_bf16 v[4:7], v[88:91], v[56:59], v[4:7]
	v_mfma_f32_16x16x32_bf16 v[0:3], v[92:95], v[56:59], v[0:3]
	s_waitcnt lgkmcnt(15)
	v_mfma_f32_16x16x32_bf16 v[4:7], v[96:99], v[60:63], v[4:7]
	v_mfma_f32_16x16x32_bf16 v[0:3], v[100:103], v[60:63], v[0:3]
	s_waitcnt lgkmcnt(15)
	v_mfma_f32_16x16x32_bf16 v[4:7], v[104:107], v[64:67], v[4:7]
	v_mfma_f32_16x16x32_bf16 v[0:3], v[108:111], v[64:67], v[0:3]
	s_waitcnt lgkmcnt(12)
	v_mfma_f32_16x16x32_bf16 v[4:7], v[112:115], v[68:71], v[4:7]
	v_mfma_f32_16x16x32_bf16 v[0:3], v[116:119], v[68:71], v[0:3]
	s_waitcnt lgkmcnt(9)
	v_mfma_f32_16x16x32_bf16 v[4:7], v[120:123], v[72:75], v[4:7]
	v_mfma_f32_16x16x32_bf16 v[0:3], v[124:127], v[72:75], v[0:3]
	s_waitcnt lgkmcnt(6)
	v_mfma_f32_16x16x32_bf16 v[4:7], v[130:133], v[76:79], v[4:7]
	v_mfma_f32_16x16x32_bf16 v[0:3], v[134:137], v[76:79], v[0:3]
	s_waitcnt lgkmcnt(3)
	v_mfma_f32_16x16x32_bf16 v[4:7], v[138:141], v[80:83], v[4:7]
	v_mfma_f32_16x16x32_bf16 v[0:3], v[142:145], v[80:83], v[0:3]
	s_waitcnt lgkmcnt(0)
	v_mfma_f32_16x16x32_bf16 v[4:7], v[146:149], v[84:87], v[4:7]
	v_mfma_f32_16x16x32_bf16 v[0:3], v[150:153], v[84:87], v[0:3]
	s_waitcnt vmcnt(9)
	ds_write_b128 v186, v[24:27] offset:0
	s_waitcnt vmcnt(8)
	ds_write_b128 v186, v[28:31] offset:1088
	s_waitcnt vmcnt(7)
	ds_write_b128 v186, v[32:35] offset:2176
	s_waitcnt vmcnt(6)
	ds_write_b128 v186, v[36:39] offset:3264
	s_waitcnt vmcnt(5)
	ds_write_b128 v186, v[40:43] offset:4352
	s_waitcnt vmcnt(4)
	ds_write_b128 v186, v[44:47] offset:5440
	s_waitcnt vmcnt(3)
	ds_write_b128 v186, v[48:51] offset:6528
	s_waitcnt vmcnt(2)
	ds_write_b128 v186, v[52:55] offset:7616
	s_mov_b64 s[14:15], 0x800
	v_lshl_add_u64 v[254:255], v[184:185], 0, s[14:15]
	global_load_dwordx4 v[24:27], v[254:255], off
	s_mov_b64 s[14:15], 0x2800
	v_lshl_add_u64 v[254:255], v[184:185], 0, s[14:15]
	global_load_dwordx4 v[28:31], v[254:255], off
	s_mov_b64 s[14:15], 0x4800
	v_lshl_add_u64 v[254:255], v[184:185], 0, s[14:15]
	global_load_dwordx4 v[32:35], v[254:255], off
	s_mov_b64 s[14:15], 0x6800
	v_lshl_add_u64 v[254:255], v[184:185], 0, s[14:15]
	global_load_dwordx4 v[36:39], v[254:255], off
	s_mov_b64 s[14:15], 0x8800
	v_lshl_add_u64 v[254:255], v[184:185], 0, s[14:15]
	global_load_dwordx4 v[40:43], v[254:255], off
	s_mov_b64 s[14:15], 0xa800
	v_lshl_add_u64 v[254:255], v[184:185], 0, s[14:15]
	global_load_dwordx4 v[44:47], v[254:255], off
	s_mov_b64 s[14:15], 0xc800
	v_lshl_add_u64 v[254:255], v[184:185], 0, s[14:15]
	global_load_dwordx4 v[48:51], v[254:255], off
	s_mov_b64 s[14:15], 0xe800
	v_lshl_add_u64 v[254:255], v[184:185], 0, s[14:15]
	global_load_dwordx4 v[52:55], v[254:255], off
	s_waitcnt vmcnt(8)
	ds_write_b128 v179, v[168:171] offset:17408
	ds_write_b128 v179, v[172:175] offset:26112
	v_add_u32_e32 v251, 16, v178
	v_min_u32_e32 v251, 0xfff, v251
	v_or_b32_e32 v251, s6, v251
	v_mul_u32_u24_e32 v128, 0x1830, v251
	v_lshl_add_u64 v[254:255], v[252:253], 0, v[128:129]
	global_load_dwordx4 v[168:171], v[254:255], off
	v_add_u32_e32 v251, 0x110, v178
	v_min_u32_e32 v251, 0xfff, v251
	v_or_b32_e32 v251, s6, v251
	v_mul_u32_u24_e32 v128, 0x1830, v251
	v_lshl_add_u64 v[254:255], v[252:253], 0, v[128:129]
	global_load_dwordx4 v[172:175], v[254:255], off
	s_waitcnt lgkmcnt(0)
	s_barrier
; #define MFMA16(a, b, c) __builtin_amdgcn_mfma_f32_16x16x32_bf16((a), (b), (c), 0, 0, 0)
; DI void compress_item(const Args& a, int l, int item, LAS unsigned char* lds) {
;     ...
; #pragma unroll 1
;     for (int k8 = 0; k8 < 64; k8 += 8) {
;         bf16x8 bfr[8], af[8][2];
; #pragma unroll
;         for (int kk = 0; kk < 8; ++kk) {
;             const int ks = k8 + kk, tokoff = ks >> 1, dcol = (ks & 1) * 32 + fq * 8;
;             bfr[kk] = *(const bf16x8*)(w1 + ks * 32);
; #pragma unroll
;             for (int m = 0; m < 2; ++m) { int tk = tk0[m] + tokoff; tk = tk > SEQ - 1 ? SEQ - 1 : tk; af[kk][m] = *(const bf16x8*)(PROJ + ((size_t)b * SEQ + tk) * PP + colbase + dcol); }
;         }
; #pragma unroll
;         for (int kk = 0; kk < 8; ++kk)
; #pragma unroll
;             for (int m = 0; m < 2; ++m) acc[m] = MFMA16(af[kk][m], bfr[kk], acc[m]);
;     }
	ds_read_b128 v[88:91], v180 offset:17408
	ds_read_b128 v[92:95], v180 offset:26112
	ds_read_b128 v[56:59], v187 offset:0
	ds_read_b128 v[96:99], v180 offset:17472
	ds_read_b128 v[100:103], v180 offset:26176
	ds_read_b128 v[60:63], v187 offset:64
	ds_read_b128 v[104:107], v180 offset:17536
	ds_read_b128 v[108:111], v180 offset:26240
	ds_read_b128 v[64:67], v187 offset:128
	ds_read_b128 v[112:115], v180 offset:17600
	ds_read_b128 v[116:119], v180 offset:26304
	ds_read_b128 v[68:71], v187 offset:192
	ds_read_b128 v[120:123], v180 offset:17664
	ds_read_b128 v[124:127], v180 offset:26368
	ds_read_b128 v[72:75], v187 offset:256
	ds_read_b128 v[130:133], v180 offset:17728
	ds_read_b128 v[134:137], v180 offset:26432
	ds_read_b128 v[76:79], v187 offset:320
	ds_read_b128 v[138:141], v180 offset:17792
	ds_read_b128 v[142:145], v180 offset:26496
	ds_read_b128 v[80:83], v187 offset:384
	ds_read_b128 v[146:149], v180 offset:17856
	ds_read_b128 v[150:153], v180 offset:26560
	ds_read_b128 v[84:87], v187 offset:448
	s_waitcnt lgkmcnt(15)
	v_mfma_f32_16x16x32_bf16 v[4:7], v[88:91], v[56:59], v[4:7]
	v_mfma_f32_16x16x32_bf16 v[0:3], v[92:95], v[56:59], v[0:3]
	s_waitcnt lgkmcnt(15)
	v_mfma_f32_16x16x32_bf16 v[4:7], v[96:99], v[60:63], v[4:7]
	v_mfma_f32_16x16x32_bf16 v[0:3], v[100:103], v[60:63], v[0:3]
	s_waitcnt lgkmcnt(15)
	v_mfma_f32_16x16x32_bf16 v[4:7], v[104:107], v[64:67], v[4:7]
	v_mfma_f32_16x16x32_bf16 v[0:3], v[108:111], v[64:67], v[0:3]
	s_waitcnt lgkmcnt(12)
	v_mfma_f32_16x16x32_bf16 v[4:7], v[112:115], v[68:71], v[4:7]
	v_mfma_f32_16x16x32_bf16 v[0:3], v[116:119], v[68:71], v[0:3]
	s_waitcnt lgkmcnt(9)
	v_mfma_f32_16x16x32_bf16 v[4:7], v[120:123], v[72:75], v[4:7]
	v_mfma_f32_16x16x32_bf16 v[0:3], v[124:127], v[72:75], v[0:3]
	s_waitcnt lgkmcnt(6)
	v_mfma_f32_16x16x32_bf16 v[4:7], v[130:133], v[76:79], v[4:7]
	v_mfma_f32_16x16x32_bf16 v[0:3], v[134:137], v[76:79], v[0:3]
	s_waitcnt lgkmcnt(3)
	v_mfma_f32_16x16x32_bf16 v[4:7], v[138:141], v[80:83], v[4:7]
	v_mfma_f32_16x16x32_bf16 v[0:3], v[142:145], v[80:83], v[0:3]
	s_waitcnt lgkmcnt(0)
	v_mfma_f32_16x16x32_bf16 v[4:7], v[146:149], v[84:87], v[4:7]
	v_mfma_f32_16x16x32_bf16 v[0:3], v[150:153], v[84:87], v[0:3]
	s_waitcnt vmcnt(9)
	ds_write_b128 v186, v[24:27] offset:0
	s_waitcnt vmcnt(8)
	ds_write_b128 v186, v[28:31] offset:1088
	s_waitcnt vmcnt(7)
	ds_write_b128 v186, v[32:35] offset:2176
	s_waitcnt vmcnt(6)
	ds_write_b128 v186, v[36:39] offset:3264
	s_waitcnt vmcnt(5)
	ds_write_b128 v186, v[40:43] offset:4352
	s_waitcnt vmcnt(4)
	ds_write_b128 v186, v[44:47] offset:5440
	s_waitcnt vmcnt(3)
	ds_write_b128 v186, v[48:51] offset:6528
	s_waitcnt vmcnt(2)
	ds_write_b128 v186, v[52:55] offset:7616
	s_mov_b64 s[14:15], 0xa00
	v_lshl_add_u64 v[254:255], v[184:185], 0, s[14:15]
	global_load_dwordx4 v[24:27], v[254:255], off
	s_mov_b64 s[14:15], 0x2a00
	v_lshl_add_u64 v[254:255], v[184:185], 0, s[14:15]
	global_load_dwordx4 v[28:31], v[254:255], off
	s_mov_b64 s[14:15], 0x4a00
	v_lshl_add_u64 v[254:255], v[184:185], 0, s[14:15]
	global_load_dwordx4 v[32:35], v[254:255], off
	s_mov_b64 s[14:15], 0x6a00
	v_lshl_add_u64 v[254:255], v[184:185], 0, s[14:15]
	global_load_dwordx4 v[36:39], v[254:255], off
	s_mov_b64 s[14:15], 0x8a00
	v_lshl_add_u64 v[254:255], v[184:185], 0, s[14:15]
	global_load_dwordx4 v[40:43], v[254:255], off
	s_mov_b64 s[14:15], 0xaa00
	v_lshl_add_u64 v[254:255], v[184:185], 0, s[14:15]
	global_load_dwordx4 v[44:47], v[254:255], off
	s_mov_b64 s[14:15], 0xca00
	v_lshl_add_u64 v[254:255], v[184:185], 0, s[14:15]
	global_load_dwordx4 v[48:51], v[254:255], off
	s_mov_b64 s[14:15], 0xea00
	v_lshl_add_u64 v[254:255], v[184:185], 0, s[14:15]
	global_load_dwordx4 v[52:55], v[254:255], off
	s_waitcnt vmcnt(8)
	ds_write_b128 v179, v[168:171] offset:0
	ds_write_b128 v179, v[172:175] offset:8704
	v_add_u32_e32 v251, 20, v178
	v_min_u32_e32 v251, 0xfff, v251
	v_or_b32_e32 v251, s6, v251
	v_mul_u32_u24_e32 v128, 0x1830, v251
	v_lshl_add_u64 v[254:255], v[252:253], 0, v[128:129]
	global_load_dwordx4 v[168:171], v[254:255], off
	v_add_u32_e32 v251, 0x114, v178
	v_min_u32_e32 v251, 0xfff, v251
	v_or_b32_e32 v251, s6, v251
	v_mul_u32_u24_e32 v128, 0x1830, v251
	v_lshl_add_u64 v[254:255], v[252:253], 0, v[128:129]
	global_load_dwordx4 v[172:175], v[254:255], off
	s_waitcnt lgkmcnt(0)
	s_barrier
; #define MFMA16(a, b, c) __builtin_amdgcn_mfma_f32_16x16x32_bf16((a), (b), (c), 0, 0, 0)
; DI void compress_item(const Args& a, int l, int item, LAS unsigned char* lds) {
;     ...
; #pragma unroll 1
;     for (int k8 = 0; k8 < 64; k8 += 8) {
;         bf16x8 bfr[8], af[8][2];
; #pragma unroll
;         for (int kk = 0; kk < 8; ++kk) {
;             const int ks = k8 + kk, tokoff = ks >> 1, dcol = (ks & 1) * 32 + fq * 8;
;             bfr[kk] = *(const bf16x8*)(w1 + ks * 32);
; #pragma unroll
;             for (int m = 0; m < 2; ++m) { int tk = tk0[m] + tokoff; tk = tk > SEQ - 1 ? SEQ - 1 : tk; af[kk][m] = *(const bf16x8*)(PROJ + ((size_t)b * SEQ + tk) * PP + colbase + dcol); }
;         }
; #pragma unroll
;         for (int kk = 0; kk < 8; ++kk)
; #pragma unroll
;             for (int m = 0; m < 2; ++m) acc[m] = MFMA16(af[kk][m], bfr[kk], acc[m]);
;     }
	ds_read_b128 v[88:91], v180 offset:0
	ds_read_b128 v[92:95], v180 offset:8704
	ds_read_b128 v[56:59], v187 offset:0
	ds_read_b128 v[96:99], v180 offset:64
	ds_read_b128 v[100:103], v180 offset:8768
	ds_read_b128 v[60:63], v187 offset:64
	ds_read_b128 v[104:107], v180 offset:128
	ds_read_b128 v[108:111], v180 offset:8832
	ds_read_b128 v[64:67], v187 offset:128
	ds_read_b128 v[112:115], v180 offset:192
	ds_read_b128 v[116:119], v180 offset:8896
	ds_read_b128 v[68:71], v187 offset:192
	ds_read_b128 v[120:123], v180 offset:256
	ds_read_b128 v[124:127], v180 offset:8960
	ds_read_b128 v[72:75], v187 offset:256
	ds_read_b128 v[130:133], v180 offset:320
	ds_read_b128 v[134:137], v180 offset:9024
	ds_read_b128 v[76:79], v187 offset:320
	ds_read_b128 v[138:141], v180 offset:384
	ds_read_b128 v[142:145], v180 offset:9088
	ds_read_b128 v[80:83], v187 offset:384
	ds_read_b128 v[146:149], v180 offset:448
	ds_read_b128 v[150:153], v180 offset:9152
	ds_read_b128 v[84:87], v187 offset:448
	s_waitcnt lgkmcnt(15)
	v_mfma_f32_16x16x32_bf16 v[4:7], v[88:91], v[56:59], v[4:7]
	v_mfma_f32_16x16x32_bf16 v[0:3], v[92:95], v[56:59], v[0:3]
	s_waitcnt lgkmcnt(15)
	v_mfma_f32_16x16x32_bf16 v[4:7], v[96:99], v[60:63], v[4:7]
	v_mfma_f32_16x16x32_bf16 v[0:3], v[100:103], v[60:63], v[0:3]
	s_waitcnt lgkmcnt(15)
	v_mfma_f32_16x16x32_bf16 v[4:7], v[104:107], v[64:67], v[4:7]
	v_mfma_f32_16x16x32_bf16 v[0:3], v[108:111], v[64:67], v[0:3]
	s_waitcnt lgkmcnt(12)
	v_mfma_f32_16x16x32_bf16 v[4:7], v[112:115], v[68:71], v[4:7]
	v_mfma_f32_16x16x32_bf16 v[0:3], v[116:119], v[68:71], v[0:3]
	s_waitcnt lgkmcnt(9)
	v_mfma_f32_16x16x32_bf16 v[4:7], v[120:123], v[72:75], v[4:7]
	v_mfma_f32_16x16x32_bf16 v[0:3], v[124:127], v[72:75], v[0:3]
	s_waitcnt lgkmcnt(6)
	v_mfma_f32_16x16x32_bf16 v[4:7], v[130:133], v[76:79], v[4:7]
	v_mfma_f32_16x16x32_bf16 v[0:3], v[134:137], v[76:79], v[0:3]
	s_waitcnt lgkmcnt(3)
	v_mfma_f32_16x16x32_bf16 v[4:7], v[138:141], v[80:83], v[4:7]
	v_mfma_f32_16x16x32_bf16 v[0:3], v[142:145], v[80:83], v[0:3]
	s_waitcnt lgkmcnt(0)
	v_mfma_f32_16x16x32_bf16 v[4:7], v[146:149], v[84:87], v[4:7]
	v_mfma_f32_16x16x32_bf16 v[0:3], v[150:153], v[84:87], v[0:3]
	s_waitcnt vmcnt(9)
	ds_write_b128 v186, v[24:27] offset:0
	s_waitcnt vmcnt(8)
	ds_write_b128 v186, v[28:31] offset:1088
	s_waitcnt vmcnt(7)
	ds_write_b128 v186, v[32:35] offset:2176
	s_waitcnt vmcnt(6)
	ds_write_b128 v186, v[36:39] offset:3264
	s_waitcnt vmcnt(5)
	ds_write_b128 v186, v[40:43] offset:4352
	s_waitcnt vmcnt(4)
	ds_write_b128 v186, v[44:47] offset:5440
	s_waitcnt vmcnt(3)
	ds_write_b128 v186, v[48:51] offset:6528
	s_waitcnt vmcnt(2)
	ds_write_b128 v186, v[52:55] offset:7616
	s_mov_b64 s[14:15], 0xc00
	v_lshl_add_u64 v[254:255], v[184:185], 0, s[14:15]
	global_load_dwordx4 v[24:27], v[254:255], off
	s_mov_b64 s[14:15], 0x2c00
	v_lshl_add_u64 v[254:255], v[184:185], 0, s[14:15]
	global_load_dwordx4 v[28:31], v[254:255], off
	s_mov_b64 s[14:15], 0x4c00
	v_lshl_add_u64 v[254:255], v[184:185], 0, s[14:15]
	global_load_dwordx4 v[32:35], v[254:255], off
	s_mov_b64 s[14:15], 0x6c00
	v_lshl_add_u64 v[254:255], v[184:185], 0, s[14:15]
	global_load_dwordx4 v[36:39], v[254:255], off
	s_mov_b64 s[14:15], 0x8c00
	v_lshl_add_u64 v[254:255], v[184:185], 0, s[14:15]
	global_load_dwordx4 v[40:43], v[254:255], off
	s_mov_b64 s[14:15], 0xac00
	v_lshl_add_u64 v[254:255], v[184:185], 0, s[14:15]
	global_load_dwordx4 v[44:47], v[254:255], off
	s_mov_b64 s[14:15], 0xcc00
	v_lshl_add_u64 v[254:255], v[184:185], 0, s[14:15]
	global_load_dwordx4 v[48:51], v[254:255], off
	s_mov_b64 s[14:15], 0xec00
	v_lshl_add_u64 v[254:255], v[184:185], 0, s[14:15]
	global_load_dwordx4 v[52:55], v[254:255], off
	s_waitcnt vmcnt(8)
	ds_write_b128 v179, v[168:171] offset:17408
	ds_write_b128 v179, v[172:175] offset:26112
	v_add_u32_e32 v251, 24, v178
	v_min_u32_e32 v251, 0xfff, v251
	v_or_b32_e32 v251, s6, v251
	v_mul_u32_u24_e32 v128, 0x1830, v251
	v_lshl_add_u64 v[254:255], v[252:253], 0, v[128:129]
	global_load_dwordx4 v[168:171], v[254:255], off
	v_add_u32_e32 v251, 0x118, v178
	v_min_u32_e32 v251, 0xfff, v251
	v_or_b32_e32 v251, s6, v251
	v_mul_u32_u24_e32 v128, 0x1830, v251
	v_lshl_add_u64 v[254:255], v[252:253], 0, v[128:129]
	global_load_dwordx4 v[172:175], v[254:255], off
	s_waitcnt lgkmcnt(0)
	s_barrier
; #define MFMA16(a, b, c) __builtin_amdgcn_mfma_f32_16x16x32_bf16((a), (b), (c), 0, 0, 0)
; DI void compress_item(const Args& a, int l, int item, LAS unsigned char* lds) {
;     ...
; #pragma unroll 1
;     for (int k8 = 0; k8 < 64; k8 += 8) {
;         bf16x8 bfr[8], af[8][2];
; #pragma unroll
;         for (int kk = 0; kk < 8; ++kk) {
;             const int ks = k8 + kk, tokoff = ks >> 1, dcol = (ks & 1) * 32 + fq * 8;
;             bfr[kk] = *(const bf16x8*)(w1 + ks * 32);
; #pragma unroll
;             for (int m = 0; m < 2; ++m) { int tk = tk0[m] + tokoff; tk = tk > SEQ - 1 ? SEQ - 1 : tk; af[kk][m] = *(const bf16x8*)(PROJ + ((size_t)b * SEQ + tk) * PP + colbase + dcol); }
;         }
; #pragma unroll
;         for (int kk = 0; kk < 8; ++kk)
; #pragma unroll
;             for (int m = 0; m < 2; ++m) acc[m] = MFMA16(af[kk][m], bfr[kk], acc[m]);
;     }
	ds_read_b128 v[88:91], v180 offset:17408
	ds_read_b128 v[92:95], v180 offset:26112
	ds_read_b128 v[56:59], v187 offset:0
	ds_read_b128 v[96:99], v180 offset:17472
	ds_read_b128 v[100:103], v180 offset:26176
	ds_read_b128 v[60:63], v187 offset:64
	ds_read_b128 v[104:107], v180 offset:17536
	ds_read_b128 v[108:111], v180 offset:26240
	ds_read_b128 v[64:67], v187 offset:128
	ds_read_b128 v[112:115], v180 offset:17600
	ds_read_b128 v[116:119], v180 offset:26304
	ds_read_b128 v[68:71], v187 offset:192
	ds_read_b128 v[120:123], v180 offset:17664
	ds_read_b128 v[124:127], v180 offset:26368
	ds_read_b128 v[72:75], v187 offset:256
	ds_read_b128 v[130:133], v180 offset:17728
	ds_read_b128 v[134:137], v180 offset:26432
	ds_read_b128 v[76:79], v187 offset:320
	ds_read_b128 v[138:141], v180 offset:17792
	ds_read_b128 v[142:145], v180 offset:26496
	ds_read_b128 v[80:83], v187 offset:384
	ds_read_b128 v[146:149], v180 offset:17856
	ds_read_b128 v[150:153], v180 offset:26560
	ds_read_b128 v[84:87], v187 offset:448
	s_waitcnt lgkmcnt(15)
	v_mfma_f32_16x16x32_bf16 v[4:7], v[88:91], v[56:59], v[4:7]
	v_mfma_f32_16x16x32_bf16 v[0:3], v[92:95], v[56:59], v[0:3]
	s_waitcnt lgkmcnt(15)
	v_mfma_f32_16x16x32_bf16 v[4:7], v[96:99], v[60:63], v[4:7]
	v_mfma_f32_16x16x32_bf16 v[0:3], v[100:103], v[60:63], v[0:3]
	s_waitcnt lgkmcnt(15)
	v_mfma_f32_16x16x32_bf16 v[4:7], v[104:107], v[64:67], v[4:7]
	v_mfma_f32_16x16x32_bf16 v[0:3], v[108:111], v[64:67], v[0:3]
	s_waitcnt lgkmcnt(12)
	v_mfma_f32_16x16x32_bf16 v[4:7], v[112:115], v[68:71], v[4:7]
	v_mfma_f32_16x16x32_bf16 v[0:3], v[116:119], v[68:71], v[0:3]
	s_waitcnt lgkmcnt(9)
	v_mfma_f32_16x16x32_bf16 v[4:7], v[120:123], v[72:75], v[4:7]
	v_mfma_f32_16x16x32_bf16 v[0:3], v[124:127], v[72:75], v[0:3]
	s_waitcnt lgkmcnt(6)
	v_mfma_f32_16x16x32_bf16 v[4:7], v[130:133], v[76:79], v[4:7]
	v_mfma_f32_16x16x32_bf16 v[0:3], v[134:137], v[76:79], v[0:3]
	s_waitcnt lgkmcnt(3)
	v_mfma_f32_16x16x32_bf16 v[4:7], v[138:141], v[80:83], v[4:7]
	v_mfma_f32_16x16x32_bf16 v[0:3], v[142:145], v[80:83], v[0:3]
	s_waitcnt lgkmcnt(0)
	v_mfma_f32_16x16x32_bf16 v[4:7], v[146:149], v[84:87], v[4:7]
	v_mfma_f32_16x16x32_bf16 v[0:3], v[150:153], v[84:87], v[0:3]
	s_waitcnt vmcnt(9)
	ds_write_b128 v186, v[24:27] offset:0
	s_waitcnt vmcnt(8)
	ds_write_b128 v186, v[28:31] offset:1088
	s_waitcnt vmcnt(7)
	ds_write_b128 v186, v[32:35] offset:2176
	s_waitcnt vmcnt(6)
	ds_write_b128 v186, v[36:39] offset:3264
	s_waitcnt vmcnt(5)
	ds_write_b128 v186, v[40:43] offset:4352
	s_waitcnt vmcnt(4)
	ds_write_b128 v186, v[44:47] offset:5440
	s_waitcnt vmcnt(3)
	ds_write_b128 v186, v[48:51] offset:6528
	s_waitcnt vmcnt(2)
	ds_write_b128 v186, v[52:55] offset:7616
	s_mov_b64 s[14:15], 0xe00
	v_lshl_add_u64 v[254:255], v[184:185], 0, s[14:15]
	global_load_dwordx4 v[24:27], v[254:255], off
	s_mov_b64 s[14:15], 0x2e00
	v_lshl_add_u64 v[254:255], v[184:185], 0, s[14:15]
	global_load_dwordx4 v[28:31], v[254:255], off
	s_mov_b64 s[14:15], 0x4e00
	v_lshl_add_u64 v[254:255], v[184:185], 0, s[14:15]
	global_load_dwordx4 v[32:35], v[254:255], off
	s_mov_b64 s[14:15], 0x6e00
	v_lshl_add_u64 v[254:255], v[184:185], 0, s[14:15]
	global_load_dwordx4 v[36:39], v[254:255], off
	s_mov_b64 s[14:15], 0x8e00
	v_lshl_add_u64 v[254:255], v[184:185], 0, s[14:15]
	global_load_dwordx4 v[40:43], v[254:255], off
	s_mov_b64 s[14:15], 0xae00
	v_lshl_add_u64 v[254:255], v[184:185], 0, s[14:15]
	global_load_dwordx4 v[44:47], v[254:255], off
	s_mov_b64 s[14:15], 0xce00
	v_lshl_add_u64 v[254:255], v[184:185], 0, s[14:15]
	global_load_dwordx4 v[48:51], v[254:255], off
	s_mov_b64 s[14:15], 0xee00
	v_lshl_add_u64 v[254:255], v[184:185], 0, s[14:15]
	global_load_dwordx4 v[52:55], v[254:255], off
	s_waitcnt vmcnt(8)
	ds_write_b128 v179, v[168:171] offset:0
	ds_write_b128 v179, v[172:175] offset:8704
	v_add_u32_e32 v251, 28, v178
	v_min_u32_e32 v251, 0xfff, v251
	v_or_b32_e32 v251, s6, v251
	v_mul_u32_u24_e32 v128, 0x1830, v251
	v_lshl_add_u64 v[254:255], v[252:253], 0, v[128:129]
	global_load_dwordx4 v[168:171], v[254:255], off
	v_add_u32_e32 v251, 0x11c, v178
	v_min_u32_e32 v251, 0xfff, v251
	v_or_b32_e32 v251, s6, v251
	v_mul_u32_u24_e32 v128, 0x1830, v251
	v_lshl_add_u64 v[254:255], v[252:253], 0, v[128:129]
	global_load_dwordx4 v[172:175], v[254:255], off
	s_waitcnt lgkmcnt(0)
	s_barrier
; #define MFMA16(a, b, c) __builtin_amdgcn_mfma_f32_16x16x32_bf16((a), (b), (c), 0, 0, 0)
; DI void compress_item(const Args& a, int l, int item, LAS unsigned char* lds) {
;     ...
; #pragma unroll 1
;     for (int k8 = 0; k8 < 64; k8 += 8) {
;         bf16x8 bfr[8], af[8][2];
; #pragma unroll
;         for (int kk = 0; kk < 8; ++kk) {
;             const int ks = k8 + kk, tokoff = ks >> 1, dcol = (ks & 1) * 32 + fq * 8;
;             bfr[kk] = *(const bf16x8*)(w1 + ks * 32);
; #pragma unroll
;             for (int m = 0; m < 2; ++m) { int tk = tk0[m] + tokoff; tk = tk > SEQ - 1 ? SEQ - 1 : tk; af[kk][m] = *(const bf16x8*)(PROJ + ((size_t)b * SEQ + tk) * PP + colbase + dcol); }
;         }
; #pragma unroll
;         for (int kk = 0; kk < 8; ++kk)
; #pragma unroll
;             for (int m = 0; m < 2; ++m) acc[m] = MFMA16(af[kk][m], bfr[kk], acc[m]);
;     }
;     {
;         const int c = wid * 16 + fr; const float* biasp = (const float*)(a.ws + WS_BIASP) + kv * 16 * 128 + c;
;         float bias = 0.f;
; #pragma unroll
;         for (int kp = 0; kp < 16; ++kp) bias += biasp[kp * 128];
	ds_read_b128 v[88:91], v180 offset:0
	ds_read_b128 v[92:95], v180 offset:8704
	ds_read_b128 v[56:59], v187 offset:0
	ds_read_b128 v[96:99], v180 offset:64
	ds_read_b128 v[100:103], v180 offset:8768
	ds_read_b128 v[60:63], v187 offset:64
	ds_read_b128 v[104:107], v180 offset:128
	ds_read_b128 v[108:111], v180 offset:8832
	ds_read_b128 v[64:67], v187 offset:128
	ds_read_b128 v[112:115], v180 offset:192
	ds_read_b128 v[116:119], v180 offset:8896
	ds_read_b128 v[68:71], v187 offset:192
	ds_read_b128 v[120:123], v180 offset:256
	ds_read_b128 v[124:127], v180 offset:8960
	ds_read_b128 v[72:75], v187 offset:256
	ds_read_b128 v[130:133], v180 offset:320
	ds_read_b128 v[134:137], v180 offset:9024
	ds_read_b128 v[76:79], v187 offset:320
	ds_read_b128 v[138:141], v180 offset:384
	ds_read_b128 v[142:145], v180 offset:9088
	ds_read_b128 v[80:83], v187 offset:384
	ds_read_b128 v[146:149], v180 offset:448
	ds_read_b128 v[150:153], v180 offset:9152
	ds_read_b128 v[84:87], v187 offset:448
	s_waitcnt lgkmcnt(15)
	v_mfma_f32_16x16x32_bf16 v[4:7], v[88:91], v[56:59], v[4:7]
	v_mfma_f32_16x16x32_bf16 v[0:3], v[92:95], v[56:59], v[0:3]
	s_waitcnt lgkmcnt(15)
	v_mfma_f32_16x16x32_bf16 v[4:7], v[96:99], v[60:63], v[4:7]
	v_mfma_f32_16x16x32_bf16 v[0:3], v[100:103], v[60:63], v[0:3]
	s_waitcnt lgkmcnt(15)
	v_mfma_f32_16x16x32_bf16 v[4:7], v[104:107], v[64:67], v[4:7]
	v_mfma_f32_16x16x32_bf16 v[0:3], v[108:111], v[64:67], v[0:3]
	s_waitcnt lgkmcnt(12)
	v_mfma_f32_16x16x32_bf16 v[4:7], v[112:115], v[68:71], v[4:7]
	v_mfma_f32_16x16x32_bf16 v[0:3], v[116:119], v[68:71], v[0:3]
	s_waitcnt lgkmcnt(9)
	v_mfma_f32_16x16x32_bf16 v[4:7], v[120:123], v[72:75], v[4:7]
	v_mfma_f32_16x16x32_bf16 v[0:3], v[124:127], v[72:75], v[0:3]
	s_waitcnt lgkmcnt(6)
	v_mfma_f32_16x16x32_bf16 v[4:7], v[130:133], v[76:79], v[4:7]
	v_mfma_f32_16x16x32_bf16 v[0:3], v[134:137], v[76:79], v[0:3]
	s_waitcnt lgkmcnt(3)
	v_mfma_f32_16x16x32_bf16 v[4:7], v[138:141], v[80:83], v[4:7]
	v_mfma_f32_16x16x32_bf16 v[0:3], v[142:145], v[80:83], v[0:3]
	s_waitcnt lgkmcnt(0)
	v_mfma_f32_16x16x32_bf16 v[4:7], v[146:149], v[84:87], v[4:7]
	v_mfma_f32_16x16x32_bf16 v[0:3], v[150:153], v[84:87], v[0:3]
	s_waitcnt vmcnt(9)
	ds_write_b128 v186, v[24:27] offset:0
	s_waitcnt vmcnt(8)
	ds_write_b128 v186, v[28:31] offset:1088
	s_waitcnt vmcnt(7)
	ds_write_b128 v186, v[32:35] offset:2176
	s_waitcnt vmcnt(6)
	ds_write_b128 v186, v[36:39] offset:3264
	s_waitcnt vmcnt(5)
	ds_write_b128 v186, v[40:43] offset:4352
	s_waitcnt vmcnt(4)
	ds_write_b128 v186, v[44:47] offset:5440
	s_waitcnt vmcnt(3)
	ds_write_b128 v186, v[48:51] offset:6528
	s_waitcnt vmcnt(2)
	ds_write_b128 v186, v[52:55] offset:7616
	s_waitcnt vmcnt(0)
	ds_write_b128 v179, v[168:171] offset:17408
	ds_write_b128 v179, v[172:175] offset:26112
	s_waitcnt lgkmcnt(0)
	s_barrier
	ds_read_b128 v[88:91], v180 offset:17408
	ds_read_b128 v[92:95], v180 offset:26112
	ds_read_b128 v[56:59], v187 offset:0
	ds_read_b128 v[96:99], v180 offset:17472
	ds_read_b128 v[100:103], v180 offset:26176
	ds_read_b128 v[60:63], v187 offset:64
	ds_read_b128 v[104:107], v180 offset:17536
	ds_read_b128 v[108:111], v180 offset:26240
	ds_read_b128 v[64:67], v187 offset:128
	ds_read_b128 v[112:115], v180 offset:17600
	ds_read_b128 v[116:119], v180 offset:26304
	ds_read_b128 v[68:71], v187 offset:192
	ds_read_b128 v[120:123], v180 offset:17664
	ds_read_b128 v[124:127], v180 offset:26368
	ds_read_b128 v[72:75], v187 offset:256
	ds_read_b128 v[130:133], v180 offset:17728
	ds_read_b128 v[134:137], v180 offset:26432
	ds_read_b128 v[76:79], v187 offset:320
	ds_read_b128 v[138:141], v180 offset:17792
	ds_read_b128 v[142:145], v180 offset:26496
	ds_read_b128 v[80:83], v187 offset:384
	ds_read_b128 v[146:149], v180 offset:17856
	ds_read_b128 v[150:153], v180 offset:26560
	ds_read_b128 v[84:87], v187 offset:448
	s_waitcnt lgkmcnt(15)
	v_mfma_f32_16x16x32_bf16 v[4:7], v[88:91], v[56:59], v[4:7]
	v_mfma_f32_16x16x32_bf16 v[0:3], v[92:95], v[56:59], v[0:3]
	s_waitcnt lgkmcnt(15)
	v_mfma_f32_16x16x32_bf16 v[4:7], v[96:99], v[60:63], v[4:7]
	v_mfma_f32_16x16x32_bf16 v[0:3], v[100:103], v[60:63], v[0:3]
	s_waitcnt lgkmcnt(15)
	v_mfma_f32_16x16x32_bf16 v[4:7], v[104:107], v[64:67], v[4:7]
	v_mfma_f32_16x16x32_bf16 v[0:3], v[108:111], v[64:67], v[0:3]
	s_waitcnt lgkmcnt(12)
	v_mfma_f32_16x16x32_bf16 v[4:7], v[112:115], v[68:71], v[4:7]
	v_mfma_f32_16x16x32_bf16 v[0:3], v[116:119], v[68:71], v[0:3]
	s_waitcnt lgkmcnt(9)
	v_mfma_f32_16x16x32_bf16 v[4:7], v[120:123], v[72:75], v[4:7]
	v_mfma_f32_16x16x32_bf16 v[0:3], v[124:127], v[72:75], v[0:3]
	s_waitcnt lgkmcnt(6)
	v_mfma_f32_16x16x32_bf16 v[4:7], v[130:133], v[76:79], v[4:7]
	v_mfma_f32_16x16x32_bf16 v[0:3], v[134:137], v[76:79], v[0:3]
	s_waitcnt lgkmcnt(3)
	v_mfma_f32_16x16x32_bf16 v[4:7], v[138:141], v[80:83], v[4:7]
	v_mfma_f32_16x16x32_bf16 v[0:3], v[142:145], v[80:83], v[0:3]
	s_waitcnt lgkmcnt(0)
	v_mfma_f32_16x16x32_bf16 v[4:7], v[146:149], v[84:87], v[4:7]
	v_mfma_f32_16x16x32_bf16 v[0:3], v[150:153], v[84:87], v[0:3]
	s_lshl_b32 s6, s4, 11
	s_ashr_i32 s7, s6, 31
	s_lshl_b64 s[6:7], s[6:7], 2
	v_readlane_b32 s14, v245, 14
	v_readlane_b32 s15, v245, 15
	s_add_u32 s6, s14, s6
	s_addc_u32 s7, s15, s7
	v_lshl_add_u64 v[12:13], v[10:11], 2, s[6:7]
	global_load_dword v11, v[12:13], off
	global_load_dword v14, v[12:13], off offset:512
	s_movk_i32 s6, 0x1000
	v_lshlrev_b32_e32 v10, 1, v10
	s_lshl_b64 s[4:5], s[4:5], 14
	v_bfe_u32 v16, v9, 6, 2
	s_waitcnt vmcnt(1)
	v_add_f32_e32 v11, 0, v11
	s_waitcnt vmcnt(0)
	v_add_f32_e32 v11, v11, v14
	global_load_dword v14, v[12:13], off offset:1024
	s_waitcnt vmcnt(0)
; DI bf16_t tobf(float x) { return (bf16_t)(pk2(x, 0.f) & 0xffffu); }
; DI float gelu_tanh(float x) { const float u = 0.7978845608f * (x + 0.044715f * x * x * x); return 0.5f * x * (1.f + tanh_fast(u)); }
; DI void compress_item(const Args& a, int l, int item, LAS unsigned char* lds) {
;     ...
;         const int c = wid * 16 + fr; const float* biasp = (const float*)(a.ws + WS_BIASP) + kv * 16 * 128 + c;
;         float bias = 0.f;
; #pragma unroll
;         for (int kp = 0; kp < 16; ++kp) bias += biasp[kp * 128];
; #pragma unroll
;         for (int m = 0; m < 2; ++m)
; #pragma unroll
;             for (int r = 0; r < 4; ++r) hs[(m * 16 + fq * 4 + r) * 136 + c] = tobf(gelu_tanh(acc[m][r] + bias));
	v_add_f32_e32 v11, v11, v14
	global_load_dword v14, v[12:13], off offset:1536
	s_waitcnt vmcnt(0)
	v_add_f32_e32 v11, v11, v14
	global_load_dword v14, v[12:13], off offset:2048
	s_waitcnt vmcnt(0)
	v_add_f32_e32 v11, v11, v14
	global_load_dword v14, v[12:13], off offset:2560
	s_waitcnt vmcnt(0)
	v_add_f32_e32 v11, v11, v14
	global_load_dword v14, v[12:13], off offset:3072
	s_waitcnt vmcnt(0)
	v_add_f32_e32 v11, v11, v14
	global_load_dword v14, v[12:13], off offset:3584
	v_add_co_u32_e32 v12, vcc, s6, v12
	s_movk_i32 s6, 0x110
	s_nop 0
	v_addc_co_u32_e32 v13, vcc, 0, v13, vcc
	s_waitcnt vmcnt(0)
	v_add_f32_e32 v11, v11, v14
	global_load_dword v14, v[12:13], off
	s_waitcnt vmcnt(0)
	v_add_f32_e32 v11, v11, v14
	global_load_dword v14, v[12:13], off offset:512
	s_waitcnt vmcnt(0)
	v_add_f32_e32 v11, v11, v14
	global_load_dword v14, v[12:13], off offset:1024
	s_waitcnt vmcnt(0)
	v_add_f32_e32 v11, v11, v14
	global_load_dword v14, v[12:13], off offset:1536
	s_waitcnt vmcnt(0)
	v_add_f32_e32 v11, v11, v14
	global_load_dword v14, v[12:13], off offset:2048
	s_waitcnt vmcnt(0)
	v_add_f32_e32 v11, v11, v14
	global_load_dword v14, v[12:13], off offset:2560
	s_waitcnt vmcnt(0)
	v_add_f32_e32 v11, v11, v14
	global_load_dword v14, v[12:13], off offset:3072
	s_waitcnt vmcnt(0)
	v_add_f32_e32 v11, v11, v14
	global_load_dword v12, v[12:13], off offset:3584
	s_waitcnt vmcnt(0)
	v_add_f32_e32 v11, v11, v12
	v_add_f32_e32 v4, v4, v11
	v_mul_f32_e32 v12, 0x3d372713, v4
	v_mul_f32_e32 v12, v4, v12
	v_fma_f32 v12, v4, v12, v4
	v_mul_f32_e32 v12, 0x3f4c422a, v12
	v_add_f32_e32 v12, v12, v12
	v_mul_f32_e32 v12, 0x3fb8aa3b, v12
	v_exp_f32_e32 v12, v12
	v_mul_f32_e32 v4, 0.5, v4
	v_add_f32_e32 v5, v5, v11
	v_add_f32_e32 v0, v0, v11
	v_add_f32_e32 v12, 1.0, v12
	v_rcp_f32_e32 v12, v12
	s_nop 0
	v_fma_f32 v12, v12, -2.0, 1.0
	v_add_f32_e32 v12, 1.0, v12
	v_mul_f32_e32 v4, v4, v12
	v_cvt_pk_bf16_f32 v12, v4, s0
	v_mul_u32_u24_e32 v4, 0x440, v20
	v_add3_u32 v4, 0, v10, v4
	v_mul_f32_e32 v10, 0x3d372713, v5
	v_mul_f32_e32 v10, v5, v10
	v_fma_f32 v10, v5, v10, v5
	v_mul_f32_e32 v10, 0x3f4c422a, v10
	v_add_f32_e32 v10, v10, v10
	v_mul_f32_e32 v10, 0x3fb8aa3b, v10
	v_exp_f32_e32 v10, v10
	v_mul_f32_e32 v5, 0.5, v5
	ds_write_b16 v4, v12
	v_add_f32_e32 v10, 1.0, v10
	v_rcp_f32_e32 v10, v10
	s_nop 0
	v_fma_f32 v10, v10, -2.0, 1.0
	v_add_f32_e32 v10, 1.0, v10
	v_mul_f32_e32 v5, v5, v10
	v_cvt_pk_bf16_f32 v5, v5, s0
	ds_write_b16 v4, v5 offset:272
	v_add_f32_e32 v5, v6, v11
	v_mul_f32_e32 v6, 0x3d372713, v5
	v_mul_f32_e32 v6, v5, v6
	v_fma_f32 v6, v5, v6, v5
	v_mul_f32_e32 v6, 0x3f4c422a, v6
	v_add_f32_e32 v6, v6, v6
	v_mul_f32_e32 v6, 0x3fb8aa3b, v6
	v_exp_f32_e32 v6, v6
	v_mul_f32_e32 v5, 0.5, v5
	v_add_f32_e32 v6, 1.0, v6
	v_rcp_f32_e32 v6, v6
	s_nop 0
	v_fma_f32 v6, v6, -2.0, 1.0
	v_add_f32_e32 v6, 1.0, v6
	v_mul_f32_e32 v5, v5, v6
	v_cvt_pk_bf16_f32 v5, v5, s0
	ds_write_b16 v4, v5 offset:544
	v_add_f32_e32 v5, v7, v11
	v_mul_f32_e32 v6, 0x3d372713, v5
	v_mul_f32_e32 v6, v5, v6
	v_fma_f32 v6, v5, v6, v5
	v_mul_f32_e32 v6, 0x3f4c422a, v6
	v_add_f32_e32 v6, v6, v6
	v_mul_f32_e32 v6, 0x3fb8aa3b, v6
	v_exp_f32_e32 v6, v6
	v_mul_f32_e32 v5, 0.5, v5
	v_add_f32_e32 v6, 1.0, v6
	v_rcp_f32_e32 v6, v6
	s_nop 0
	v_fma_f32 v6, v6, -2.0, 1.0
	v_add_f32_e32 v6, 1.0, v6
	v_mul_f32_e32 v5, v5, v6
	v_cvt_pk_bf16_f32 v5, v5, s0
	ds_write_b16 v4, v5 offset:816
	v_mul_f32_e32 v5, 0x3d372713, v0
	v_mul_f32_e32 v5, v0, v5
	v_fma_f32 v5, v0, v5, v0
	v_mul_f32_e32 v5, 0x3f4c422a, v5
	v_add_f32_e32 v5, v5, v5
	v_mul_f32_e32 v5, 0x3fb8aa3b, v5
	v_exp_f32_e32 v5, v5
	v_mul_f32_e32 v0, 0.5, v0
	v_add_f32_e32 v5, 1.0, v5
	v_rcp_f32_e32 v5, v5
	s_nop 0
	v_fma_f32 v5, v5, -2.0, 1.0
	v_add_f32_e32 v5, 1.0, v5
	v_mul_f32_e32 v0, v0, v5
	v_cvt_pk_bf16_f32 v0, v0, s0
	ds_write_b16 v4, v0 offset:4352
	v_add_f32_e32 v0, v1, v11
	v_mul_f32_e32 v1, 0x3d372713, v0
	v_mul_f32_e32 v1, v0, v1
	v_fma_f32 v1, v0, v1, v0
	v_mul_f32_e32 v1, 0x3f4c422a, v1
	v_add_f32_e32 v1, v1, v1
	v_mul_f32_e32 v1, 0x3fb8aa3b, v1
	v_exp_f32_e32 v1, v1
	v_mul_f32_e32 v0, 0.5, v0
	v_add_f32_e32 v1, 1.0, v1
	v_rcp_f32_e32 v1, v1
	s_nop 0
	v_fma_f32 v1, v1, -2.0, 1.0
	v_add_f32_e32 v1, 1.0, v1
	v_mul_f32_e32 v0, v0, v1
	v_cvt_pk_bf16_f32 v0, v0, s0
	ds_write_b16 v4, v0 offset:4624
	v_add_f32_e32 v0, v2, v11
	v_mul_f32_e32 v1, 0x3d372713, v0
	v_mul_f32_e32 v1, v0, v1
	v_fma_f32 v1, v0, v1, v0
	v_mul_f32_e32 v1, 0x3f4c422a, v1
	v_add_f32_e32 v1, v1, v1
	v_mul_f32_e32 v1, 0x3fb8aa3b, v1
	v_exp_f32_e32 v1, v1
	v_mul_f32_e32 v0, 0.5, v0
	v_add_f32_e32 v1, 1.0, v1
	v_rcp_f32_e32 v1, v1
	s_nop 0
	v_fma_f32 v1, v1, -2.0, 1.0
	v_add_f32_e32 v1, 1.0, v1
	v_mul_f32_e32 v0, v0, v1
	v_cvt_pk_bf16_f32 v0, v0, s0
	ds_write_b16 v4, v0 offset:4896
	v_add_f32_e32 v0, v3, v11
	v_mul_f32_e32 v1, 0x3d372713, v0
	v_mul_f32_e32 v1, v0, v1
	v_fma_f32 v1, v0, v1, v0
	v_mul_f32_e32 v1, 0x3f4c422a, v1
	v_add_f32_e32 v1, v1, v1
	v_mul_f32_e32 v1, 0x3fb8aa3b, v1
	v_exp_f32_e32 v1, v1
	v_mul_f32_e32 v0, 0.5, v0
	v_add_f32_e32 v1, 1.0, v1
	v_rcp_f32_e32 v1, v1
	s_nop 0
	v_fma_f32 v1, v1, -2.0, 1.0
	v_add_f32_e32 v1, 1.0, v1
	v_mul_f32_e32 v0, v0, v1
	v_cvt_pk_bf16_f32 v0, v0, s0
	ds_write_b16 v4, v0 offset:5168
	v_ashrrev_i32_e32 v0, 4, v9
	v_and_b32_e32 v17, -16, v0
	v_or_b32_e32 v0, v17, v21
	v_mul_lo_u32 v1, v0, s6
	v_lshlrev_b32_e32 v0, 1, v8
	v_readlane_b32 s6, v245, 52
	v_add3_u32 v8, 0, v1, v0
	v_readlane_b32 s7, v245, 53
	s_add_u32 s4, s6, s4
	v_lshlrev_b32_e32 v1, 8, v21
	s_addc_u32 s5, s7, s5
	v_lshl_or_b32 v128, v16, 12, v1
	v_lshl_add_u64 v[2:3], s[4:5], 0, v[128:129]
	v_mov_b32_e32 v1, v129
	v_lshl_add_u64 v[14:15], v[2:3], 0, v[0:1]
	s_waitcnt lgkmcnt(0)
	s_barrier
; #define LAS __attribute__((address_space(3)))
; DI bf16_t tobf(float x) { return (bf16_t)(pk2(x, 0.f) & 0xffffu); }
; DI u32x4 pack8(const float* f) { u32x4 w; w.x = pk2(f[0], f[1]); w.y = pk2(f[2], f[3]); w.z = pk2(f[4], f[5]); w.w = pk2(f[6], f[7]); return w; }
; DI float red8(float x) { x = red4(x); x = dpp_add<0x141>(x); return x; }
; #define MFMA16(a, b, c) __builtin_amdgcn_mfma_f32_16x16x32_bf16((a), (b), (c), 0, 0, 0)
; DI void compress_item(const Args& a, int l, int item, LAS unsigned char* lds) {
;     ...
;     {
;         const int m = wid >> 2, nt = wid & 3;
;         f32x4 acc2 = {0.f, 0.f, 0.f, 0.f};
; #pragma unroll
;         for (int ks = 0; ks < 4; ++ks) {
;             const bf16x8 af = *(const LAS bf16x8*)(hs + (m * 16 + fr) * 136 + ks * 32 + fq * 8);
;             const bf16x8 bf = *(const bf16x8*)(W + W_C2 + (size_t)kv * 8192 + (size_t)(nt * 16 + fr) * 128 + ks * 32 + fq * 8);
;             acc2 = MFMA16(af, bf, acc2);
;         }
; #pragma unroll
;         for (int r = 0; r < 4; ++r) os[(m * 16 + fq * 4 + r) * 64 + nt * 16 + fr] = acc2[r];
;     }
;     __syncthreads();
;     if (tid < 256) {
;         const int rowi = tid >> 3, d0 = (tid & 7) * 8, n = nq * 32 + rowi;
;         float v[8];
; #pragma unroll
;         for (int i = 0; i < 8; ++i) v[i] = os[rowi * 64 + d0 + i];
;         if (kv == 0) {
;             float ss = 0.f;
; #pragma unroll
;             for (int i = 0; i < 8; ++i) ss += v[i] * v[i];
;             ss = red8(ss);
;             const float rstd = rsqrtf(ss * (1.f / 64.f) + 1e-6f);
;             const float* gn = a.in[I_KGAIN] + (l * 3 + 0) * 64 + d0;
; #pragma unroll
;             for (int i = 0; i < 8; ++i) v[i] = (n == 255) ? 0.f : v[i] * rstd * gn[i];
;             *(u32x4*)((bf16_t*)(a.ws + WS_KCN) + ((size_t)bg * 256 + n) * 64 + d0) = pack8(v);
;         } else {
;             bf16_t* vct = (bf16_t*)(a.ws + WS_VCT) + (size_t)bg * 64 * 256;
; #pragma unroll
;             for (int i = 0; i < 8; ++i) vct[(d0 + i) * 256 + n] = tobf(n == 255 ? 0.f : v[i]);
	global_load_dwordx4 v[4:7], v[14:15], off
	global_load_dwordx4 v[10:13], v[14:15], off offset:64
	ds_read_b128 v[0:3], v8
	s_waitcnt vmcnt(1) lgkmcnt(0)
	v_mfma_f32_16x16x32_bf16 v[0:3], v[0:3], v[4:7], 0
	ds_read_b128 v[4:7], v8 offset:64
	s_movk_i32 s4, 0x100
	v_cmp_gt_i32_e32 vcc, s4, v9
	s_waitcnt vmcnt(0) lgkmcnt(0)
	v_mfma_f32_16x16x32_bf16 v[0:3], v[4:7], v[10:13], v[0:3]
	global_load_dwordx4 v[10:13], v[14:15], off offset:128
	ds_read_b128 v[4:7], v8 offset:128
	s_waitcnt vmcnt(0) lgkmcnt(0)
	v_mfma_f32_16x16x32_bf16 v[0:3], v[4:7], v[10:13], v[0:3]
	global_load_dwordx4 v[10:13], v[14:15], off offset:192
	ds_read_b128 v[4:7], v8 offset:192
	s_waitcnt vmcnt(0) lgkmcnt(0)
	v_mfma_f32_16x16x32_bf16 v[0:3], v[4:7], v[10:13], v[0:3]
	v_lshlrev_b32_e32 v4, 6, v16
	v_lshlrev_b32_e32 v5, 2, v21
	v_add3_u32 v4, 0, v4, v5
	v_lshlrev_b32_e32 v5, 10, v20
	v_lshlrev_b32_e32 v6, 8, v17
	v_add3_u32 v4, v4, v5, v6
	s_nop 1
	ds_write2st64_b32 v4, v0, v1 offset0:34 offset1:35
	ds_write2st64_b32 v4, v2, v3 offset0:36 offset1:37
	s_waitcnt lgkmcnt(0)
	s_barrier
	s_and_saveexec_b64 s[4:5], vcc
	s_cbranch_execz .LBB0_598
	v_lshlrev_b32_e32 v0, 3, v9
	v_ashrrev_i32_e32 v8, 3, v9
	v_and_b32_e32 v12, 56, v0
	v_lshlrev_b32_e32 v0, 8, v8
	v_lshlrev_b32_e32 v128, 2, v12
	v_add3_u32 v0, 0, v0, v128
	ds_read_b128 v[4:7], v0 offset:8704
	ds_read_b128 v[0:3], v0 offset:8720
	s_and_b32 s6, s11, 7
	v_lshl_add_u32 v8, s6, 5, v8
	s_mov_b64 s[6:7], -1
	s_and_b64 vcc, exec, s[2:3]
	s_cbranch_vccz .LBB0_608
	s_lshl_b32 s2, s13, 15
	v_readlane_b32 s3, v245, 54
	s_add_u32 s2, s3, s2
	v_readlane_b32 s3, v245, 55
	s_movk_i32 s6, 0xff
	v_lshl_add_u32 v10, v12, 8, v8
	s_addc_u32 s3, s3, 0
	s_waitcnt lgkmcnt(1)
	v_cvt_pk_bf16_f32 v9, v4, s0
	v_cmp_eq_u32_e32 vcc, s6, v8
	v_ashrrev_i32_e32 v11, 31, v10
	v_lshl_add_u64 v[10:11], v[10:11], 1, s[2:3]
	v_cndmask_b32_e64 v9, v9, 0, vcc
	global_store_short v[10:11], v9, off
	v_cvt_pk_bf16_f32 v9, v5, s0
	v_cndmask_b32_e64 v9, v9, 0, vcc
	global_store_short v[10:11], v9, off offset:512
	v_cvt_pk_bf16_f32 v9, v6, s0
	v_cndmask_b32_e64 v9, v9, 0, vcc
	global_store_short v[10:11], v9, off offset:1024
	v_cvt_pk_bf16_f32 v9, v7, s0
	v_cndmask_b32_e64 v9, v9, 0, vcc
	global_store_short v[10:11], v9, off offset:1536
	s_waitcnt lgkmcnt(0)
	v_cvt_pk_bf16_f32 v9, v0, s0
	v_cndmask_b32_e64 v9, v9, 0, vcc
	global_store_short v[10:11], v9, off offset:2048
	v_cvt_pk_bf16_f32 v9, v1, s0
	v_cndmask_b32_e64 v9, v9, 0, vcc
	global_store_short v[10:11], v9, off offset:2560
	v_cvt_pk_bf16_f32 v9, v2, s0
	v_cndmask_b32_e64 v9, v9, 0, vcc
	global_store_short v[10:11], v9, off offset:3072
	v_cvt_pk_bf16_f32 v9, v3, s0
	v_cndmask_b32_e64 v9, v9, 0, vcc
	global_store_short v[10:11], v9, off offset:3584
	s_mov_b64 s[6:7], 0
